# in_even GEMM unit order: heavy q|k|v tiles in round 1, light b|c|hv tiles in round 2 (no workgroup gets two heavy tiles); 6 whole row panels per XCD
# speedup vs baseline: 1.0765x; 1.0021x over previous
.LBB0_344:
	v_readlane_b32 s0, v254, 16
	v_readlane_b32 s1, v254, 17
	s_andn2_b64 vcc, exec, s[0:1]
	s_cbranch_vccnz .LBB0_530
	v_readlane_b32 s0, v254, 34
	v_mov_b32_e32 v8, v224
	v_readlane_b32 s48, v254, 0
	v_mov_b32_e32 v0, s0
	v_readlane_b32 s0, v254, 35
	ds_read_b128 v[0:3], v0
	v_readlane_b32 s50, v254, 1
	v_mov_b32_e32 v4, s0
	ds_read2_b64 v[4:7], v4 offset1:1
	s_ashr_i32 s51, s48, 31
	s_cmpk_lt_i32 s48, 0x1b0
	s_cselect_b64 s[2:3], -1, 0
	s_waitcnt lgkmcnt(0)
	v_readfirstlane_b32 s42, v3
	v_readfirstlane_b32 s43, v2
	v_readfirstlane_b32 s4, v1
	v_readfirstlane_b32 s5, v0
	v_readfirstlane_b32 s44, v5
	v_readfirstlane_b32 s45, v4
	v_readfirstlane_b32 s46, v7
	v_readfirstlane_b32 s47, v6
	v_readfirstlane_b32 s49, v8
	s_and_b64 vcc, exec, s[2:3]
	s_cbranch_vccz .LBB0_347
	s_cmp_lt_u32 s48, 0x90
	s_cbranch_scc1 .Lie_heavy_a
	s_sub_u32 s6, s48, 0x90
	s_and_b32 s7, s6, 7
	s_lshr_b32 s6, s6, 3
	s_mul_i32 s7, s7, 36
	s_add_u32 s6, s6, s7
	s_mul_i32 s7, s6, 0xaaab
	s_lshr_b32 s0, s7, 18
	s_mul_i32 s7, s0, 6
	s_sub_u32 s20, s6, s7
	s_add_u32 s20, s20, 3
	s_branch .Lie_done_a
.Lie_heavy_a:
	s_and_b32 s7, s48, 7
	s_lshr_b32 s6, s48, 3
	s_mul_i32 s7, s7, 18
	s_add_u32 s6, s6, s7
	s_mul_i32 s7, s6, 0xaaab
	s_lshr_b32 s0, s7, 17
	s_mul_i32 s7, s0, 3
	s_sub_u32 s20, s6, s7
.Lie_done_a:
.LBB0_347:
	s_andn2_b64 vcc, exec, s[2:3]
	s_cbranch_vccnz .LBB0_495
	v_ashrrev_i32_e32 v1, 31, v8
	v_lshrrev_b32_e32 v1, 26, v1
	v_add_u32_e32 v1, v8, v1
	v_ashrrev_i32_e32 v9, 6, v1
	v_bfe_i32 v1, v8, 27, 1
	v_lshlrev_b32_e32 v0, 4, v8
	v_lshrrev_b32_e32 v1, 22, v1
	v_add_u32_e32 v1, v0, v1
	v_and_b32_e32 v1, 0xfffffc00, v1
	v_sub_u32_e32 v1, v0, v1
	v_lshrrev_b32_e32 v2, 4, v1
	v_bitop3_b32 v1, v2, v1, 32 bitop3:0x6c
	v_ashrrev_i32_e32 v3, 31, v1
	v_lshrrev_b32_e32 v3, 26, v3
	v_add_u32_e32 v3, v1, v3
	v_ashrrev_i32_e32 v10, 6, v3
	v_and_b32_e32 v3, 0xc0, v3
	v_sub_u32_e32 v1, v1, v3
	v_lshlrev_b32_e32 v2, 3, v9
	v_lshlrev_b32_e32 v4, 5, v9
	v_ashrrev_i16_sdwa v1, v229, sext(v1) dst_sel:DWORD dst_unused:UNUSED_PAD src0_sel:DWORD src1_sel:BYTE_0
	v_and_b32_e32 v2, 0x1ffff0, v2
	v_and_b32_e32 v4, 32, v4
	v_bfe_i32 v11, v1, 0, 16
	v_add_u32_e32 v1, v4, v11
	v_add_lshl_u32 v2, v10, v2, 11
	v_add_u32_e32 v0, 0x2000, v0
	v_lshl_add_u32 v160, v1, 1, v2
	v_ashrrev_i32_e32 v1, 31, v0
	v_lshrrev_b32_e32 v1, 22, v1
	v_add_u32_e32 v1, v0, v1
	v_ashrrev_i32_e32 v12, 10, v1
	v_mul_i32_i24_e32 v1, 0x400, v12
	v_sub_u32_e32 v0, v0, v1
	v_lshrrev_b32_e32 v1, 4, v0
	v_bitop3_b32 v0, v1, v0, 32 bitop3:0x6c
	v_ashrrev_i32_e32 v2, 31, v0
	s_add_u32 s52, s43, 0xc582000
	v_lshrrev_b32_e32 v2, 26, v2
	s_addc_u32 s53, s42, 0
	s_ashr_i32 s8, s49, 6
	v_add_u32_e32 v2, v0, v2
	s_ashr_i32 s1, s0, 31
	s_ashr_i32 s21, s20, 31
	v_ashrrev_i32_e32 v13, 6, v2
	v_and_b32_e32 v2, 0xc0, v2
	s_ashr_i32 s9, s49, 8
	s_lshl_b32 s54, s8, 10
	s_lshl_b64 s[6:7], s[0:1], 19
	s_lshl_b64 s[2:3], s[20:21], 19
	v_sub_u32_e32 v0, v0, v2
	s_add_u32 s2, s43, s2
	v_lshlrev_b32_e32 v1, 3, v12
	v_lshlrev_b32_e32 v3, 5, v12
	v_ashrrev_i16_sdwa v0, v229, sext(v0) dst_sel:DWORD dst_unused:UNUSED_PAD src0_sel:DWORD src1_sel:BYTE_0
	s_addc_u32 s3, s42, s3
	s_add_i32 s21, s54, 0
	v_and_b32_e32 v1, 0x1ffff0, v1
	v_and_b32_e32 v3, 32, v3
	v_bfe_i32 v14, v0, 0, 16
	s_add_i32 m0, s21, 0x10000
	v_add_u32_e32 v0, v3, v14
	v_add_lshl_u32 v1, v13, v1, 11
	global_load_lds_dwordx4 v160, s[2:3]
	s_add_i32 m0, s21, 0x12000
	v_lshl_add_u32 v162, v0, 1, v1
	s_add_u32 s6, s52, s6
	global_load_lds_dwordx4 v162, s[2:3]
	s_addc_u32 s7, s53, s7
	s_mov_b32 m0, s21
	s_add_i32 s55, s21, 0x2000
	global_load_lds_dwordx4 v160, s[6:7]
	s_mov_b32 m0, s55
	s_add_u32 s10, s2, 0x40000
	global_load_lds_dwordx4 v162, s[6:7]
	s_addc_u32 s11, s3, 0
	s_add_i32 m0, s21, 0x14000
	v_mov_b32_e32 v161, v169
	global_load_lds_dwordx4 v160, s[10:11]
	s_add_i32 m0, s21, 0x16000
	v_mov_b32_e32 v163, v169
	global_load_lds_dwordx4 v162, s[10:11]
	s_add_u32 s10, s6, 0x40000
	s_addc_u32 s11, s7, 0
	s_add_i32 s56, s21, 0x4000
	s_mov_b32 m0, s56
	s_add_i32 s57, s21, 0x6000
	global_load_lds_dwordx4 v160, s[10:11]
	s_mov_b32 m0, s57
	v_lshl_add_u64 v[6:7], s[2:3], 0, v[160:161]
	global_load_lds_dwordx4 v162, s[10:11]
	v_lshl_add_u64 v[4:5], s[2:3], 0, v[162:163]
	v_lshl_add_u64 v[2:3], s[6:7], 0, v[160:161]
	s_cmp_lg_u32 s9, 1
	v_lshl_add_u64 v[0:1], s[6:7], 0, v[162:163]
	s_cbranch_scc1 .LBB0_350
	s_barrier

.LBB0_352:
	s_add_i32 s63, s63, 1
	s_mul_i32 s1, s63, s62
	s_mul_hi_u32 s4, s63, s50
	s_add_i32 s4, s4, s1
	s_mul_i32 s1, s63, s50
	s_add_u32 s8, s1, s48
	s_addc_u32 s9, s4, s51
	v_mov_b64_e32 v[0:1], 0x1af
	v_cmp_gt_i64_e64 s[4:5], s[8:9], v[0:1]
	s_and_b64 vcc, exec, s[4:5]
	s_cbranch_vccnz .LBB0_354
	s_cmp_lt_u32 s8, 0x90
	s_cbranch_scc1 .Lie_heavy_b
	s_sub_u32 s34, s8, 0x90
	s_and_b32 s35, s34, 7
	s_lshr_b32 s34, s34, 3
	s_mul_i32 s35, s35, 36
	s_add_u32 s34, s34, s35
	s_mul_i32 s35, s34, 0xaaab
	s_lshr_b32 s30, s35, 18
	s_mul_i32 s35, s30, 6
	s_sub_u32 s28, s34, s35
	s_add_u32 s28, s28, 3
	s_branch .Lie_done_b
.Lie_heavy_b:
	s_and_b32 s35, s8, 7
	s_lshr_b32 s34, s8, 3
	s_mul_i32 s35, s35, 18
	s_add_u32 s34, s34, s35
	s_mul_i32 s35, s34, 0xaaab
	s_lshr_b32 s30, s35, 17
	s_mul_i32 s35, s30, 3
	s_sub_u32 s28, s34, s35
.Lie_done_b:
.LBB0_354:
	s_ashr_i32 s31, s30, 31
	v_cmp_lt_i64_e32 vcc, s[8:9], v[170:171]
	s_lshl_b64 s[8:9], s[30:31], 19
	s_add_u32 s34, s52, s8
	s_addc_u32 s35, s53, s9
	s_and_b64 s[8:9], vcc, exec
	s_cselect_b32 s1, s35, s7
	s_cselect_b32 s31, s34, s6
	s_ashr_i32 s29, s28, 31
	s_lshl_b64 s[8:9], s[28:29], 19
	s_add_u32 s36, s43, s8
	s_addc_u32 s37, s42, s9
	s_and_b64 s[8:9], vcc, exec
	s_cselect_b32 s29, s37, s3
	s_cselect_b32 s38, s36, s2
	s_add_u32 s6, s6, 0x40080
	s_addc_u32 s7, s7, 0
	s_add_u32 s39, s2, 0x100
	s_addc_u32 s40, s3, 0
	s_mov_b32 s41, -2
	s_add_u32 s2, s6, 0xfffc0080
	s_addc_u32 s3, s7, -1
	s_add_i32 s64, 0, 0x10000
	v_add_u32_e32 v140, s64, v208
	ds_read_b128 v[128:131], v140
	ds_read_b128 v[132:135], v140 offset:1024
	ds_read_b128 v[136:139], v140 offset:2048
	ds_read_b128 v[140:143], v140 offset:3072
	s_cmp_eq_u32 s41, 12
	s_cselect_b32 s9, s1, s3
	s_cselect_b32 s8, s31, s2
	s_cselect_b32 s3, s29, s40
	s_cselect_b32 s2, s38, s39
	v_lshl_add_u64 v[196:197], s[6:7], 0, v[164:165]
	s_add_i32 m0, s21, 0xc000
	ds_read_b128 v[144:147], v209
	ds_read_b128 v[148:151], v209 offset:1024
	ds_read_b128 v[152:155], v209 offset:2048
	ds_read_b128 v[156:159], v209 offset:3072
	ds_read_b128 v[180:183], v209 offset:4096
	ds_read_b128 v[184:187], v209 offset:5120
	ds_read_b128 v[188:191], v209 offset:6144
	ds_read_b128 v[192:195], v209 offset:7168
	global_load_lds_dwordx4 v[196:197], off
	v_lshl_add_u64 v[196:197], s[6:7], 0, v[166:167]
	s_add_i32 m0, s21, 0xe000
	s_nop 0
	global_load_lds_dwordx4 v[196:197], off
	s_waitcnt lgkmcnt(8)
	s_barrier
	s_waitcnt lgkmcnt(0)
	s_setprio 1
	s_waitcnt lgkmcnt(0)
	v_mfma_f32_16x16x32_bf16 v[124:127], v[128:131], v[144:147], 0
	v_mfma_f32_16x16x32_bf16 v[120:123], v[136:139], v[144:147], 0
	v_mfma_f32_16x16x32_bf16 v[116:119], v[128:131], v[152:155], 0
	v_mfma_f32_16x16x32_bf16 v[112:115], v[136:139], v[152:155], 0
	v_mfma_f32_16x16x32_bf16 v[100:103], v[128:131], v[180:183], 0
	v_mfma_f32_16x16x32_bf16 v[96:99], v[136:139], v[180:183], 0
	v_mfma_f32_16x16x32_bf16 v[84:87], v[128:131], v[188:191], 0
	v_mfma_f32_16x16x32_bf16 v[80:83], v[136:139], v[188:191], 0
	v_mfma_f32_16x16x32_bf16 v[124:127], v[132:135], v[148:151], v[124:127]
	v_mfma_f32_16x16x32_bf16 v[120:123], v[140:143], v[148:151], v[120:123]
	v_mfma_f32_16x16x32_bf16 v[116:119], v[132:135], v[156:159], v[116:119]
	v_mfma_f32_16x16x32_bf16 v[112:115], v[140:143], v[156:159], v[112:115]
	v_mfma_f32_16x16x32_bf16 v[100:103], v[132:135], v[184:187], v[100:103]
	v_mfma_f32_16x16x32_bf16 v[96:99], v[140:143], v[184:187], v[96:99]
	v_mfma_f32_16x16x32_bf16 v[84:87], v[132:135], v[192:195], v[84:87]
	v_mfma_f32_16x16x32_bf16 v[80:83], v[140:143], v[192:195], v[80:83]
	s_setprio 0
	s_barrier
	s_add_i32 s66, 0, 0x14000
	s_add_i32 s64, s64, s54
	v_add_u32_e32 v168, s66, v208
	v_lshl_add_u64 v[204:205], s[2:3], 0, v[160:161]
	s_mov_b32 m0, s64
	ds_read_b128 v[196:199], v168
	ds_read_b128 v[200:203], v168 offset:1024
	ds_read_b128 v[210:213], v168 offset:2048
	ds_read_b128 v[214:217], v168 offset:3072
	global_load_lds_dwordx4 v[204:205], off
	v_lshl_add_u64 v[218:219], s[2:3], 0, v[162:163]
	s_add_i32 m0, s64, 0x2000
	s_nop 0
	global_load_lds_dwordx4 v[218:219], off
	s_barrier
	s_waitcnt lgkmcnt(0)
	s_setprio 1
	s_waitcnt lgkmcnt(0)
	v_mfma_f32_16x16x32_bf16 v[108:111], v[196:199], v[144:147], 0
	v_mfma_f32_16x16x32_bf16 v[104:107], v[210:213], v[144:147], 0
	v_mfma_f32_16x16x32_bf16 v[92:95], v[196:199], v[152:155], 0
	v_mfma_f32_16x16x32_bf16 v[88:91], v[210:213], v[152:155], 0
	v_mfma_f32_16x16x32_bf16 v[76:79], v[196:199], v[180:183], 0
	v_mfma_f32_16x16x32_bf16 v[72:75], v[210:213], v[180:183], 0
	v_mfma_f32_16x16x32_bf16 v[68:71], v[196:199], v[188:191], 0
	v_mfma_f32_16x16x32_bf16 v[64:67], v[210:213], v[188:191], 0
	v_mfma_f32_16x16x32_bf16 v[108:111], v[200:203], v[148:151], v[108:111]
	v_mfma_f32_16x16x32_bf16 v[104:107], v[214:217], v[148:151], v[104:107]
	v_mfma_f32_16x16x32_bf16 v[92:95], v[200:203], v[156:159], v[92:95]
	v_mfma_f32_16x16x32_bf16 v[88:91], v[214:217], v[156:159], v[88:91]
	v_mfma_f32_16x16x32_bf16 v[76:79], v[200:203], v[184:187], v[76:79]
	v_mfma_f32_16x16x32_bf16 v[72:75], v[214:217], v[184:187], v[72:75]
	v_mfma_f32_16x16x32_bf16 v[68:71], v[200:203], v[192:195], v[68:71]
	v_mfma_f32_16x16x32_bf16 v[64:67], v[214:217], v[192:195], v[64:67]
	s_setprio 0
	s_mov_b32 m0, s21
	v_lshl_add_u64 v[220:221], s[8:9], 0, v[160:161]
	s_barrier
	ds_read_b128 v[144:147], v209 offset:16384
	ds_read_b128 v[148:151], v209 offset:17408
	ds_read_b128 v[152:155], v209 offset:18432
	ds_read_b128 v[156:159], v209 offset:19456
	ds_read_b128 v[180:183], v209 offset:20480
	ds_read_b128 v[184:187], v209 offset:21504
	ds_read_b128 v[188:191], v209 offset:22528
	ds_read_b128 v[192:195], v209 offset:23552
	global_load_lds_dwordx4 v[220:221], off
	v_lshl_add_u64 v[222:223], s[8:9], 0, v[162:163]
	s_mov_b32 m0, s55
	s_nop 0
	global_load_lds_dwordx4 v[222:223], off
	s_barrier
	s_waitcnt lgkmcnt(0)
	s_setprio 1
	s_waitcnt lgkmcnt(0)
	v_mfma_f32_16x16x32_bf16 v[60:63], v[128:131], v[144:147], 0
	v_mfma_f32_16x16x32_bf16 v[56:59], v[136:139], v[144:147], 0
	v_mfma_f32_16x16x32_bf16 v[52:55], v[128:131], v[152:155], 0
	v_mfma_f32_16x16x32_bf16 v[48:51], v[136:139], v[152:155], 0
	v_mfma_f32_16x16x32_bf16 v[36:39], v[128:131], v[180:183], 0
	v_mfma_f32_16x16x32_bf16 v[32:35], v[136:139], v[180:183], 0
	v_mfma_f32_16x16x32_bf16 v[20:23], v[128:131], v[188:191], 0
	v_mfma_f32_16x16x32_bf16 v[16:19], v[136:139], v[188:191], 0
	v_mfma_f32_16x16x32_bf16 v[60:63], v[132:135], v[148:151], v[60:63]
	v_mfma_f32_16x16x32_bf16 v[56:59], v[140:143], v[148:151], v[56:59]
	v_mfma_f32_16x16x32_bf16 v[52:55], v[132:135], v[156:159], v[52:55]
	v_mfma_f32_16x16x32_bf16 v[48:51], v[140:143], v[156:159], v[48:51]
	v_mfma_f32_16x16x32_bf16 v[36:39], v[132:135], v[184:187], v[36:39]
	v_mfma_f32_16x16x32_bf16 v[32:35], v[140:143], v[184:187], v[32:35]
	v_mfma_f32_16x16x32_bf16 v[20:23], v[132:135], v[192:195], v[20:23]
	v_mfma_f32_16x16x32_bf16 v[16:19], v[140:143], v[192:195], v[16:19]
	s_setprio 0
	s_barrier
	s_add_u32 s64, s2, 0x40000
	s_addc_u32 s65, s3, 0
	s_add_i32 s66, s66, s54
	v_lshl_add_u64 v[128:129], s[64:65], 0, v[160:161]
	s_mov_b32 m0, s66
	s_nop 0
	global_load_lds_dwordx4 v[128:129], off
	v_lshl_add_u64 v[128:129], s[64:65], 0, v[162:163]
	s_add_i32 m0, s66, 0x2000
	s_nop 0
	global_load_lds_dwordx4 v[128:129], off
	s_waitcnt vmcnt(6)
	s_barrier
	s_setprio 1
	v_mfma_f32_16x16x32_bf16 v[44:47], v[196:199], v[144:147], 0
	v_mfma_f32_16x16x32_bf16 v[40:43], v[210:213], v[144:147], 0
	v_mfma_f32_16x16x32_bf16 v[28:31], v[196:199], v[152:155], 0
	v_mfma_f32_16x16x32_bf16 v[24:27], v[210:213], v[152:155], 0
	v_mfma_f32_16x16x32_bf16 v[12:15], v[196:199], v[180:183], 0
	v_mfma_f32_16x16x32_bf16 v[8:11], v[210:213], v[180:183], 0
	v_mfma_f32_16x16x32_bf16 v[4:7], v[196:199], v[188:191], 0
	v_mfma_f32_16x16x32_bf16 v[0:3], v[210:213], v[188:191], 0
	v_mfma_f32_16x16x32_bf16 v[44:47], v[200:203], v[148:151], v[44:47]
	v_mfma_f32_16x16x32_bf16 v[40:43], v[214:217], v[148:151], v[40:43]
	v_mfma_f32_16x16x32_bf16 v[28:31], v[200:203], v[156:159], v[28:31]
	v_mfma_f32_16x16x32_bf16 v[24:27], v[214:217], v[156:159], v[24:27]
	v_mfma_f32_16x16x32_bf16 v[12:15], v[200:203], v[184:187], v[12:15]
	v_mfma_f32_16x16x32_bf16 v[8:11], v[214:217], v[184:187], v[8:11]
	v_mfma_f32_16x16x32_bf16 v[4:7], v[200:203], v[192:195], v[4:7]
	v_mfma_f32_16x16x32_bf16 v[0:3], v[214:217], v[192:195], v[0:3]
	s_setprio 0
	s_add_i32 s64, 0, 0x18000
	v_add_u32_e32 v140, s64, v208
	s_barrier
	ds_read_b128 v[128:131], v140
	ds_read_b128 v[132:135], v140 offset:1024
	ds_read_b128 v[136:139], v140 offset:2048
	ds_read_b128 v[140:143], v140 offset:3072
	s_add_u32 s8, s8, 0x40000
	s_addc_u32 s9, s9, 0
	s_mov_b32 m0, s56
	v_lshl_add_u64 v[196:197], s[8:9], 0, v[160:161]
	ds_read_b128 v[144:147], v209 offset:32768
	ds_read_b128 v[148:151], v209 offset:33792
	ds_read_b128 v[152:155], v209 offset:34816
	ds_read_b128 v[156:159], v209 offset:35840
	ds_read_b128 v[180:183], v209 offset:36864
	ds_read_b128 v[184:187], v209 offset:37888
	ds_read_b128 v[188:191], v209 offset:38912
	ds_read_b128 v[192:195], v209 offset:39936
	global_load_lds_dwordx4 v[196:197], off
	v_lshl_add_u64 v[196:197], s[8:9], 0, v[162:163]
	s_mov_b32 m0, s57
	s_nop 0
	global_load_lds_dwordx4 v[196:197], off
	s_waitcnt lgkmcnt(8)
	s_barrier
	s_waitcnt lgkmcnt(0)
	s_setprio 1
	s_waitcnt lgkmcnt(0)
	v_mfma_f32_16x16x32_bf16 v[124:127], v[128:131], v[144:147], v[124:127]
	v_mfma_f32_16x16x32_bf16 v[120:123], v[136:139], v[144:147], v[120:123]
	v_mfma_f32_16x16x32_bf16 v[116:119], v[128:131], v[152:155], v[116:119]
	v_mfma_f32_16x16x32_bf16 v[112:115], v[136:139], v[152:155], v[112:115]
	v_mfma_f32_16x16x32_bf16 v[100:103], v[128:131], v[180:183], v[100:103]
	v_mfma_f32_16x16x32_bf16 v[96:99], v[136:139], v[180:183], v[96:99]
	v_mfma_f32_16x16x32_bf16 v[84:87], v[128:131], v[188:191], v[84:87]
	v_mfma_f32_16x16x32_bf16 v[80:83], v[136:139], v[188:191], v[80:83]
	v_mfma_f32_16x16x32_bf16 v[124:127], v[132:135], v[148:151], v[124:127]
	v_mfma_f32_16x16x32_bf16 v[120:123], v[140:143], v[148:151], v[120:123]
	v_mfma_f32_16x16x32_bf16 v[116:119], v[132:135], v[156:159], v[116:119]
	v_mfma_f32_16x16x32_bf16 v[112:115], v[140:143], v[156:159], v[112:115]
	v_mfma_f32_16x16x32_bf16 v[100:103], v[132:135], v[184:187], v[100:103]
	v_mfma_f32_16x16x32_bf16 v[96:99], v[140:143], v[184:187], v[96:99]
	v_mfma_f32_16x16x32_bf16 v[84:87], v[132:135], v[192:195], v[84:87]
	v_mfma_f32_16x16x32_bf16 v[80:83], v[140:143], v[192:195], v[80:83]
	s_setprio 0
	s_barrier
	s_add_i32 s8, 0, 0x1c000
	s_add_i32 s9, s64, s54
	v_add_u32_e32 v168, s8, v208
	v_lshl_add_u64 v[204:205], v[204:205], 0, s[78:79]
	s_mov_b32 m0, s9
	ds_read_b128 v[196:199], v168
	ds_read_b128 v[200:203], v168 offset:1024
	ds_read_b128 v[210:213], v168 offset:2048
	ds_read_b128 v[214:217], v168 offset:3072
	global_load_lds_dwordx4 v[204:205], off
	v_lshl_add_u64 v[204:205], v[218:219], 0, s[78:79]
	s_add_i32 m0, s9, 0x2000
	s_nop 0
	global_load_lds_dwordx4 v[204:205], off
	s_barrier
	s_waitcnt lgkmcnt(0)
	s_setprio 1
	s_waitcnt lgkmcnt(0)
	v_mfma_f32_16x16x32_bf16 v[108:111], v[196:199], v[144:147], v[108:111]
	v_mfma_f32_16x16x32_bf16 v[104:107], v[210:213], v[144:147], v[104:107]
	v_mfma_f32_16x16x32_bf16 v[92:95], v[196:199], v[152:155], v[92:95]
	v_mfma_f32_16x16x32_bf16 v[88:91], v[210:213], v[152:155], v[88:91]
	v_mfma_f32_16x16x32_bf16 v[76:79], v[196:199], v[180:183], v[76:79]
	v_mfma_f32_16x16x32_bf16 v[72:75], v[210:213], v[180:183], v[72:75]
	v_mfma_f32_16x16x32_bf16 v[68:71], v[196:199], v[188:191], v[68:71]
	v_mfma_f32_16x16x32_bf16 v[64:67], v[210:213], v[188:191], v[64:67]
	v_mfma_f32_16x16x32_bf16 v[108:111], v[200:203], v[148:151], v[108:111]
	v_mfma_f32_16x16x32_bf16 v[104:107], v[214:217], v[148:151], v[104:107]
	v_mfma_f32_16x16x32_bf16 v[92:95], v[200:203], v[156:159], v[92:95]
	v_mfma_f32_16x16x32_bf16 v[88:91], v[214:217], v[156:159], v[88:91]
	v_mfma_f32_16x16x32_bf16 v[76:79], v[200:203], v[184:187], v[76:79]
	v_mfma_f32_16x16x32_bf16 v[72:75], v[214:217], v[184:187], v[72:75]
	v_mfma_f32_16x16x32_bf16 v[68:71], v[200:203], v[192:195], v[68:71]
	v_mfma_f32_16x16x32_bf16 v[64:67], v[214:217], v[192:195], v[64:67]
	s_setprio 0
	s_mov_b32 m0, s60
	v_lshl_add_u64 v[204:205], v[220:221], 0, s[78:79]
	s_barrier
	ds_read_b128 v[144:147], v209 offset:49152
	ds_read_b128 v[148:151], v209 offset:50176
	ds_read_b128 v[152:155], v209 offset:51200
	ds_read_b128 v[156:159], v209 offset:52224
	ds_read_b128 v[180:183], v209 offset:53248
	ds_read_b128 v[184:187], v209 offset:54272
	ds_read_b128 v[188:191], v209 offset:55296
	ds_read_b128 v[192:195], v209 offset:56320
	global_load_lds_dwordx4 v[204:205], off
	v_lshl_add_u64 v[204:205], v[222:223], 0, s[78:79]
	s_mov_b32 m0, s61
	s_nop 0
	global_load_lds_dwordx4 v[204:205], off
	s_barrier
	s_waitcnt lgkmcnt(0)
	s_setprio 1
	s_waitcnt lgkmcnt(0)
	v_mfma_f32_16x16x32_bf16 v[60:63], v[128:131], v[144:147], v[60:63]
	v_mfma_f32_16x16x32_bf16 v[56:59], v[136:139], v[144:147], v[56:59]
	v_mfma_f32_16x16x32_bf16 v[52:55], v[128:131], v[152:155], v[52:55]
	v_mfma_f32_16x16x32_bf16 v[48:51], v[136:139], v[152:155], v[48:51]
	v_mfma_f32_16x16x32_bf16 v[36:39], v[128:131], v[180:183], v[36:39]
	v_mfma_f32_16x16x32_bf16 v[32:35], v[136:139], v[180:183], v[32:35]
	v_mfma_f32_16x16x32_bf16 v[20:23], v[128:131], v[188:191], v[20:23]
	v_mfma_f32_16x16x32_bf16 v[16:19], v[136:139], v[188:191], v[16:19]
	v_mfma_f32_16x16x32_bf16 v[60:63], v[132:135], v[148:151], v[60:63]
	v_mfma_f32_16x16x32_bf16 v[56:59], v[140:143], v[148:151], v[56:59]
	v_mfma_f32_16x16x32_bf16 v[52:55], v[132:135], v[156:159], v[52:55]
	v_mfma_f32_16x16x32_bf16 v[48:51], v[140:143], v[156:159], v[48:51]
	v_mfma_f32_16x16x32_bf16 v[36:39], v[132:135], v[184:187], v[36:39]
	v_mfma_f32_16x16x32_bf16 v[32:35], v[140:143], v[184:187], v[32:35]
	v_mfma_f32_16x16x32_bf16 v[20:23], v[132:135], v[192:195], v[20:23]
	v_mfma_f32_16x16x32_bf16 v[16:19], v[140:143], v[192:195], v[16:19]
	s_setprio 0
	s_barrier
	s_add_u32 s2, s2, 0x40080
	s_addc_u32 s3, s3, 0
	s_add_i32 s8, s8, s54
	v_lshl_add_u64 v[128:129], s[2:3], 0, v[160:161]
	s_mov_b32 m0, s8
	s_nop 0
	global_load_lds_dwordx4 v[128:129], off
	v_lshl_add_u64 v[128:129], s[2:3], 0, v[162:163]
	s_add_i32 m0, s8, 0x2000
	s_nop 0
	global_load_lds_dwordx4 v[128:129], off
	s_waitcnt vmcnt(6)
	s_barrier
	s_setprio 1
	v_mfma_f32_16x16x32_bf16 v[44:47], v[196:199], v[144:147], v[44:47]
	v_mfma_f32_16x16x32_bf16 v[40:43], v[210:213], v[144:147], v[40:43]
	v_mfma_f32_16x16x32_bf16 v[28:31], v[196:199], v[152:155], v[28:31]
	v_mfma_f32_16x16x32_bf16 v[24:27], v[210:213], v[152:155], v[24:27]
	v_mfma_f32_16x16x32_bf16 v[12:15], v[196:199], v[180:183], v[12:15]
	v_mfma_f32_16x16x32_bf16 v[8:11], v[210:213], v[180:183], v[8:11]
	v_mfma_f32_16x16x32_bf16 v[4:7], v[196:199], v[188:191], v[4:7]
	v_mfma_f32_16x16x32_bf16 v[0:3], v[210:213], v[188:191], v[0:3]
	v_mfma_f32_16x16x32_bf16 v[44:47], v[200:203], v[148:151], v[44:47]
	v_mfma_f32_16x16x32_bf16 v[40:43], v[214:217], v[148:151], v[40:43]
	v_mfma_f32_16x16x32_bf16 v[28:31], v[200:203], v[156:159], v[28:31]
	v_mfma_f32_16x16x32_bf16 v[24:27], v[214:217], v[156:159], v[24:27]
	v_mfma_f32_16x16x32_bf16 v[12:15], v[200:203], v[184:187], v[12:15]
	v_mfma_f32_16x16x32_bf16 v[8:11], v[214:217], v[184:187], v[8:11]
	v_mfma_f32_16x16x32_bf16 v[4:7], v[200:203], v[192:195], v[4:7]
	v_mfma_f32_16x16x32_bf16 v[0:3], v[214:217], v[192:195], v[0:3]
	s_setprio 0
	s_add_i32 s41, s41, 2
	s_add_u32 s6, s6, 0x100
	s_addc_u32 s7, s7, 0
	s_add_u32 s39, s39, 0x100
	s_addc_u32 s40, s40, 0
	s_cmp_gt_u32 s41, 13
	s_barrier
